# v20 + non-temporal hint on the remaining read-once f32 weight loads of the prologue conversion (immediate-offset forms)
# baseline (speedup 1.0000x reference)
; __device__ __forceinline__ void conv_weight(const float* W, int ldw, int K, int Nphys, int Nvalid, int mode, const float* g, bf16_t* WT, LAS float* scr, int gw, int NGW, int lane, int& rot) {
;     ...
; #pragma unroll
;         for (int i = 0; i < 32; ++i) { const int kk = 2 * i + (lane >> 5); float v = wv_[i]; if (g) v *= g[k0 + kk]; scr[kk * 33 + (lane & 31)] = v; }
.LBB0_80:
	s_or_b64 exec, exec, s[20:21]
	v_cndmask_b32_e64 v27, 0, 1, s[16:17]
	v_cmp_ne_u32_e64 s[4:5], 1, v27
	s_andn2_b64 vcc, exec, s[16:17]
	s_cbranch_vccnz .LBB0_103
	v_ashrrev_i32_e32 v27, 31, v26
	s_ashr_i32 s19, s18, 31
	v_lshl_add_u64 v[26:27], v[26:27], 2, s[14:15]
	v_lshl_add_u64 v[28:29], s[18:19], 0, v[2:3]
	v_lshl_add_u64 v[28:29], v[28:29], 2, s[14:15]
	global_load_dword v58, v[26:27], off nt
	global_load_dword v59, v[28:29], off offset:8 nt
	global_load_dword v56, v[28:29], off offset:16 nt
	global_load_dword v57, v[28:29], off offset:24 nt
	s_waitcnt vmcnt(3)
	v_mul_f32_e32 v28, v40, v58
	s_waitcnt vmcnt(2)
	v_mul_f32_e32 v29, v41, v59
	ds_write2_b32 v37, v28, v29 offset1:66
	s_waitcnt vmcnt(0)
	v_pk_mul_f32 v[26:27], v[8:9], v[56:57]
	s_cbranch_execnz .LBB0_83

; __device__ __forceinline__ void conv_weight(const float* W, int ldw, int K, int Nphys, int Nvalid, int mode, const float* g, bf16_t* WT, LAS float* scr, int gw, int NGW, int lane, int& rot) {
;     ...
; #pragma unroll
;         for (int i = 0; i < 32; ++i) { const int kk = 2 * i + (lane >> 5); float v = wv_[i]; if (g) v *= g[k0 + kk]; scr[kk * 33 + (lane & 31)] = v; }
.LBB0_83:
	s_and_b64 vcc, exec, s[4:5]
	ds_write2_b32 v33, v26, v27 offset1:66
	s_cbranch_vccnz .LBB0_104
	s_ashr_i32 s19, s18, 31
	s_waitcnt vmcnt(0)
	v_lshl_add_u64 v[8:9], s[18:19], 0, v[2:3]
	v_lshl_add_u64 v[8:9], v[8:9], 2, s[14:15]
	global_load_dword v28, v[8:9], off offset:32 nt
	global_load_dword v29, v[8:9], off offset:40 nt
	global_load_dword v26, v[8:9], off offset:48 nt
	global_load_dword v27, v[8:9], off offset:56 nt
	s_waitcnt vmcnt(3)
	v_mul_f32_e32 v28, v43, v28
	s_waitcnt vmcnt(2)
	v_mul_f32_e32 v29, v42, v29
	ds_write2_b32 v38, v28, v29 offset1:66
	s_waitcnt vmcnt(0)
	v_pk_mul_f32 v[8:9], v[10:11], v[26:27]
	s_cbranch_execnz .LBB0_86

; __device__ __forceinline__ void conv_weight(const float* W, int ldw, int K, int Nphys, int Nvalid, int mode, const float* g, bf16_t* WT, LAS float* scr, int gw, int NGW, int lane, int& rot) {
;     ...
; #pragma unroll
;         for (int i = 0; i < 32; ++i) { const int kk = 2 * i + (lane >> 5); float v = wv_[i]; if (g) v *= g[k0 + kk]; scr[kk * 33 + (lane & 31)] = v; }
.LBB0_86:
	s_and_b64 vcc, exec, s[4:5]
	s_waitcnt vmcnt(0)
	ds_write2_b32 v36, v8, v9 offset1:66
	s_cbranch_vccnz .LBB0_105
	s_ashr_i32 s19, s18, 31
	v_lshl_add_u64 v[8:9], s[18:19], 0, v[2:3]
	v_lshl_add_u64 v[8:9], v[8:9], 2, s[14:15]
	global_load_dword v26, v[8:9], off offset:64 nt
	global_load_dword v27, v[8:9], off offset:72 nt
	global_load_dword v10, v[8:9], off offset:80 nt
	global_load_dword v11, v[8:9], off offset:88 nt
	s_waitcnt vmcnt(3)
	v_mul_f32_e32 v26, v45, v26
	s_waitcnt vmcnt(2)
	v_mul_f32_e32 v27, v44, v27
	ds_write2_b32 v39, v26, v27 offset1:66
	s_waitcnt vmcnt(0)
	v_pk_mul_f32 v[8:9], v[14:15], v[10:11]
	s_cbranch_execnz .LBB0_89

; __device__ __forceinline__ void conv_weight(const float* W, int ldw, int K, int Nphys, int Nvalid, int mode, const float* g, bf16_t* WT, LAS float* scr, int gw, int NGW, int lane, int& rot) {
;     ...
; #pragma unroll
;         for (int i = 0; i < 32; ++i) { const int kk = 2 * i + (lane >> 5); float v = wv_[i]; if (g) v *= g[k0 + kk]; scr[kk * 33 + (lane & 31)] = v; }
.LBB0_89:
	s_and_b64 vcc, exec, s[4:5]
	v_add_u32_e32 v10, 0x400, v39
	ds_write2_b32 v39, v8, v9 offset0:132 offset1:198
	s_cbranch_vccnz .LBB0_106
	s_ashr_i32 s19, s18, 31
	v_lshl_add_u64 v[8:9], s[18:19], 0, v[2:3]
	v_lshl_add_u64 v[8:9], v[8:9], 2, s[14:15]
	global_load_dword v11, v[8:9], off offset:96 nt
	global_load_dword v26, v[8:9], off offset:104 nt
	global_load_dword v14, v[8:9], off offset:112 nt
	global_load_dword v15, v[8:9], off offset:120 nt
	s_waitcnt vmcnt(3)
	v_mul_f32_e32 v11, v47, v11
	s_waitcnt vmcnt(2)
	v_mul_f32_e32 v26, v46, v26
	ds_write2_b32 v10, v11, v26 offset0:8 offset1:74
	s_waitcnt vmcnt(0)
	v_pk_mul_f32 v[8:9], v[16:17], v[14:15]
	s_cbranch_execnz .LBB0_92

; __device__ __forceinline__ void conv_weight(const float* W, int ldw, int K, int Nphys, int Nvalid, int mode, const float* g, bf16_t* WT, LAS float* scr, int gw, int NGW, int lane, int& rot) {
;     ...
; #pragma unroll
;         for (int i = 0; i < 32; ++i) { const int kk = 2 * i + (lane >> 5); float v = wv_[i]; if (g) v *= g[k0 + kk]; scr[kk * 33 + (lane & 31)] = v; }
.LBB0_92:
	ds_write2_b32 v10, v8, v9 offset0:140 offset1:206
	s_and_b64 vcc, exec, s[4:5]
	v_add_u32_e32 v10, 0x800, v39
	s_cbranch_vccnz .LBB0_107
	s_ashr_i32 s19, s18, 31
	v_lshl_add_u64 v[8:9], s[18:19], 0, v[2:3]
	v_lshl_add_u64 v[8:9], v[8:9], 2, s[14:15]
	global_load_dword v11, v[8:9], off offset:128 nt
	global_load_dword v16, v[8:9], off offset:136 nt
	global_load_dword v14, v[8:9], off offset:144 nt
	global_load_dword v15, v[8:9], off offset:152 nt
	s_waitcnt vmcnt(3)
	v_mul_f32_e32 v11, v49, v11
	s_waitcnt vmcnt(2)
	v_mul_f32_e32 v16, v48, v16
	ds_write2_b32 v10, v11, v16 offset0:16 offset1:82
	s_waitcnt vmcnt(0)
	v_pk_mul_f32 v[8:9], v[20:21], v[14:15]
	s_cbranch_execnz .LBB0_95

; __device__ __forceinline__ void conv_weight(const float* W, int ldw, int K, int Nphys, int Nvalid, int mode, const float* g, bf16_t* WT, LAS float* scr, int gw, int NGW, int lane, int& rot) {
;     ...
; #pragma unroll
;         for (int i = 0; i < 32; ++i) { const int kk = 2 * i + (lane >> 5); float v = wv_[i]; if (g) v *= g[k0 + kk]; scr[kk * 33 + (lane & 31)] = v; }
.LBB0_95:
	ds_write2_b32 v10, v8, v9 offset0:148 offset1:214
	s_and_b64 vcc, exec, s[4:5]
	v_add_u32_e32 v10, 0xc00, v39
	s_cbranch_vccnz .LBB0_108
	s_ashr_i32 s19, s18, 31
	v_lshl_add_u64 v[8:9], s[18:19], 0, v[2:3]
	v_lshl_add_u64 v[8:9], v[8:9], 2, s[14:15]
	global_load_dword v11, v[8:9], off offset:160 nt
	global_load_dword v16, v[8:9], off offset:168 nt
	global_load_dword v14, v[8:9], off offset:176 nt
	global_load_dword v15, v[8:9], off offset:184 nt
	s_waitcnt vmcnt(3)
	v_mul_f32_e32 v11, v53, v11
	s_waitcnt vmcnt(2)
	v_mul_f32_e32 v16, v51, v16
	ds_write2_b32 v10, v11, v16 offset0:24 offset1:90
	s_waitcnt vmcnt(0)
	v_pk_mul_f32 v[8:9], v[22:23], v[14:15]
	s_cbranch_execnz .LBB0_98

; __device__ __forceinline__ void conv_weight(const float* W, int ldw, int K, int Nphys, int Nvalid, int mode, const float* g, bf16_t* WT, LAS float* scr, int gw, int NGW, int lane, int& rot) {
;     ...
; #pragma unroll
;         for (int i = 0; i < 32; ++i) { const int kk = 2 * i + (lane >> 5); float v = wv_[i]; if (g) v *= g[k0 + kk]; scr[kk * 33 + (lane & 31)] = v; }
.LBB0_98:
	ds_write2_b32 v10, v8, v9 offset0:156 offset1:222
	s_and_b64 vcc, exec, s[4:5]
	v_add_u32_e32 v10, 0x1000, v39
	s_cbranch_vccnz .LBB0_109
	s_ashr_i32 s19, s18, 31
	v_lshl_add_u64 v[8:9], s[18:19], 0, v[2:3]
	v_lshl_add_u64 v[8:9], v[8:9], 2, s[14:15]
	global_load_dword v11, v[8:9], off offset:192 nt
	global_load_dword v16, v[8:9], off offset:200 nt
	global_load_dword v14, v[8:9], off offset:208 nt
	global_load_dword v15, v[8:9], off offset:216 nt
	s_waitcnt vmcnt(3)
	v_mul_f32_e32 v11, v55, v11
	s_waitcnt vmcnt(2)
	v_mul_f32_e32 v16, v54, v16
	ds_write2_b32 v10, v11, v16 offset0:32 offset1:98
	s_waitcnt vmcnt(0)
	v_pk_mul_f32 v[8:9], v[24:25], v[14:15]
	s_cbranch_execnz .LBB0_101

; __device__ __forceinline__ void conv_weight(const float* W, int ldw, int K, int Nphys, int Nvalid, int mode, const float* g, bf16_t* WT, LAS float* scr, int gw, int NGW, int lane, int& rot) {
;     ...
; #pragma unroll
;         for (int i = 0; i < 32; ++i) { const int kk = 2 * i + (lane >> 5); float v = wv_[i]; if (g) v *= g[k0 + kk]; scr[kk * 33 + (lane & 31)] = v; }
.LBB0_101:
	ds_write2_b32 v10, v8, v9 offset0:164 offset1:230
	s_and_b64 vcc, exec, s[4:5]
	v_add_u32_e32 v10, 0x1400, v39
	s_cbranch_vccnz .LBB0_110
	s_ashr_i32 s19, s18, 31
	v_lshl_add_u64 v[8:9], s[18:19], 0, v[2:3]
	v_lshl_add_u64 v[8:9], v[8:9], 2, s[14:15]
	global_load_dword v11, v[8:9], off offset:224 nt
	global_load_dword v16, v[8:9], off offset:232 nt
	global_load_dword v14, v[8:9], off offset:240 nt
	global_load_dword v15, v[8:9], off offset:248 nt
	s_waitcnt vmcnt(3)
	v_mul_f32_e32 v11, v52, v11
	s_waitcnt vmcnt(2)
	v_mul_f32_e32 v16, v50, v16
	ds_write2_b32 v10, v11, v16 offset0:40 offset1:106
	s_waitcnt vmcnt(0)
	v_pk_mul_f32 v[8:9], v[12:13], v[14:15]
	s_cbranch_execnz .LBB0_5
	s_branch .LBB0_4

; __device__ __forceinline__ void conv_weight(const float* W, int ldw, int K, int Nphys, int Nvalid, int mode, const float* g, bf16_t* WT, LAS float* scr, int gw, int NGW, int lane, int& rot) {
;     ...
; #pragma unroll
;         for (int i = 0; i < 32; ++i) { const int kk = 2 * i + (lane >> 5); float v = wv_[i]; if (g) v *= g[k0 + kk]; scr[kk * 33 + (lane & 31)] = v; }
.LBB0_246:
	s_or_b64 exec, exec, s[4:5]
	v_cndmask_b32_e64 v16, 0, 1, s[14:15]
	v_cmp_ne_u32_e64 s[4:5], 1, v16
	s_andn2_b64 vcc, exec, s[14:15]
	v_add_u32_e32 v16, v30, v37
	s_cbranch_vccnz .LBB0_271
	s_ashr_i32 s17, s16, 31
	v_lshl_add_u64 v[12:13], v[12:13], 2, s[12:13]
	v_lshl_add_u64 v[60:61], s[16:17], 0, v[6:7]
	v_lshl_add_u64 v[60:61], v[60:61], 2, s[12:13]
	global_load_dword v17, v[12:13], off nt
	global_load_dword v59, v[60:61], off offset:8 nt
	global_load_dword v62, v[60:61], off offset:16 nt
	global_load_dword v63, v[60:61], off offset:24 nt
	s_waitcnt vmcnt(3)
	v_mul_f32_e32 v17, v44, v17
	s_waitcnt vmcnt(2)
	v_mul_f32_e32 v59, v46, v59
	ds_write2_b32 v16, v17, v59 offset1:66
	s_waitcnt vmcnt(0)
	v_pk_mul_f32 v[12:13], v[8:9], v[62:63]
	s_cbranch_execnz .LBB0_249

; __device__ __forceinline__ void conv_weight(const float* W, int ldw, int K, int Nphys, int Nvalid, int mode, const float* g, bf16_t* WT, LAS float* scr, int gw, int NGW, int lane, int& rot) {
;     ...
; #pragma unroll
;         for (int i = 0; i < 32; ++i) { const int kk = 2 * i + (lane >> 5); float v = wv_[i]; if (g) v *= g[k0 + kk]; scr[kk * 33 + (lane & 31)] = v; }
.LBB0_249:
	s_and_b64 vcc, exec, s[4:5]
	ds_write2_b32 v39, v12, v13 offset1:66
	s_cbranch_vccnz .LBB0_272
	s_ashr_i32 s17, s16, 31
	s_waitcnt vmcnt(0)
	v_lshl_add_u64 v[8:9], s[16:17], 0, v[6:7]
	v_lshl_add_u64 v[8:9], v[8:9], 2, s[12:13]
	global_load_dword v16, v[8:9], off offset:32 nt
	global_load_dword v17, v[8:9], off offset:40 nt
	global_load_dword v12, v[8:9], off offset:48 nt
	global_load_dword v13, v[8:9], off offset:56 nt
	s_waitcnt vmcnt(3)
	v_mul_f32_e32 v16, v43, v16
	s_waitcnt vmcnt(2)
	v_mul_f32_e32 v17, v48, v17
	ds_write2_b32 v41, v16, v17 offset1:66
	s_waitcnt vmcnt(0)
	v_pk_mul_f32 v[8:9], v[10:11], v[12:13]
	s_cbranch_execnz .LBB0_252

; __device__ __forceinline__ void conv_weight(const float* W, int ldw, int K, int Nphys, int Nvalid, int mode, const float* g, bf16_t* WT, LAS float* scr, int gw, int NGW, int lane, int& rot) {
;     ...
; #pragma unroll
;         for (int i = 0; i < 32; ++i) { const int kk = 2 * i + (lane >> 5); float v = wv_[i]; if (g) v *= g[k0 + kk]; scr[kk * 33 + (lane & 31)] = v; }
.LBB0_252:
	s_and_b64 vcc, exec, s[4:5]
	s_waitcnt vmcnt(0)
	ds_write2_b32 v40, v8, v9 offset1:66
	s_cbranch_vccnz .LBB0_273
	s_ashr_i32 s17, s16, 31
	v_lshl_add_u64 v[8:9], s[16:17], 0, v[6:7]
	v_lshl_add_u64 v[8:9], v[8:9], 2, s[12:13]
	global_load_dword v12, v[8:9], off offset:64 nt
	global_load_dword v13, v[8:9], off offset:72 nt
	global_load_dword v10, v[8:9], off offset:80 nt
	global_load_dword v11, v[8:9], off offset:88 nt
	s_waitcnt vmcnt(3)
	v_mul_f32_e32 v12, v45, v12
	s_waitcnt vmcnt(2)
	v_mul_f32_e32 v13, v50, v13
	ds_write2_b32 v42, v12, v13 offset1:66
	s_waitcnt vmcnt(0)
	v_pk_mul_f32 v[8:9], v[14:15], v[10:11]
	s_cbranch_execnz .LBB0_255

; __device__ __forceinline__ void conv_weight(const float* W, int ldw, int K, int Nphys, int Nvalid, int mode, const float* g, bf16_t* WT, LAS float* scr, int gw, int NGW, int lane, int& rot) {
;     ...
; #pragma unroll
;         for (int i = 0; i < 32; ++i) { const int kk = 2 * i + (lane >> 5); float v = wv_[i]; if (g) v *= g[k0 + kk]; scr[kk * 33 + (lane & 31)] = v; }
.LBB0_255:
	s_and_b64 vcc, exec, s[4:5]
	v_add_u32_e32 v10, 0x400, v42
	ds_write2_b32 v42, v8, v9 offset0:132 offset1:198
	s_cbranch_vccnz .LBB0_274
	s_ashr_i32 s17, s16, 31
	v_lshl_add_u64 v[8:9], s[16:17], 0, v[6:7]
	v_lshl_add_u64 v[8:9], v[8:9], 2, s[12:13]
	global_load_dword v11, v[8:9], off offset:96 nt
	global_load_dword v14, v[8:9], off offset:104 nt
	global_load_dword v12, v[8:9], off offset:112 nt
	global_load_dword v13, v[8:9], off offset:120 nt
	s_waitcnt vmcnt(3)
	v_mul_f32_e32 v11, v47, v11
	s_waitcnt vmcnt(2)
	v_mul_f32_e32 v14, v52, v14
	ds_write2_b32 v10, v11, v14 offset0:8 offset1:74
	s_waitcnt vmcnt(0)
	v_pk_mul_f32 v[8:9], v[20:21], v[12:13]
	s_cbranch_execnz .LBB0_258

; __device__ __forceinline__ void conv_weight(const float* W, int ldw, int K, int Nphys, int Nvalid, int mode, const float* g, bf16_t* WT, LAS float* scr, int gw, int NGW, int lane, int& rot) {
;     ...
; #pragma unroll
;         for (int i = 0; i < 32; ++i) { const int kk = 2 * i + (lane >> 5); float v = wv_[i]; if (g) v *= g[k0 + kk]; scr[kk * 33 + (lane & 31)] = v; }
.LBB0_258:
	ds_write2_b32 v10, v8, v9 offset0:140 offset1:206
	s_and_b64 vcc, exec, s[4:5]
	v_add_u32_e32 v10, 0x800, v42
	s_cbranch_vccnz .LBB0_275
	s_ashr_i32 s17, s16, 31
	v_lshl_add_u64 v[8:9], s[16:17], 0, v[6:7]
	v_lshl_add_u64 v[8:9], v[8:9], 2, s[12:13]
	global_load_dword v11, v[8:9], off offset:128 nt
	global_load_dword v14, v[8:9], off offset:136 nt
	global_load_dword v12, v[8:9], off offset:144 nt
	global_load_dword v13, v[8:9], off offset:152 nt
	s_waitcnt vmcnt(3)
	v_mul_f32_e32 v11, v49, v11
	s_waitcnt vmcnt(2)
	v_mul_f32_e32 v14, v54, v14
	ds_write2_b32 v10, v11, v14 offset0:16 offset1:82
	s_waitcnt vmcnt(0)
	v_pk_mul_f32 v[8:9], v[22:23], v[12:13]
	s_cbranch_execnz .LBB0_261

; __device__ __forceinline__ void conv_weight(const float* W, int ldw, int K, int Nphys, int Nvalid, int mode, const float* g, bf16_t* WT, LAS float* scr, int gw, int NGW, int lane, int& rot) {
;     ...
; #pragma unroll
;         for (int i = 0; i < 32; ++i) { const int kk = 2 * i + (lane >> 5); float v = wv_[i]; if (g) v *= g[k0 + kk]; scr[kk * 33 + (lane & 31)] = v; }
.LBB0_261:
	ds_write2_b32 v10, v8, v9 offset0:148 offset1:214
	s_and_b64 vcc, exec, s[4:5]
	v_add_u32_e32 v10, 0xc00, v42
	s_cbranch_vccnz .LBB0_276
	s_ashr_i32 s17, s16, 31
	v_lshl_add_u64 v[8:9], s[16:17], 0, v[6:7]
	v_lshl_add_u64 v[8:9], v[8:9], 2, s[12:13]
	global_load_dword v11, v[8:9], off offset:160 nt
	global_load_dword v14, v[8:9], off offset:168 nt
	global_load_dword v12, v[8:9], off offset:176 nt
	global_load_dword v13, v[8:9], off offset:184 nt
	s_waitcnt vmcnt(3)
	v_mul_f32_e32 v11, v51, v11
	s_waitcnt vmcnt(2)
	v_mul_f32_e32 v14, v56, v14
	ds_write2_b32 v10, v11, v14 offset0:24 offset1:90
	s_waitcnt vmcnt(0)
	v_pk_mul_f32 v[8:9], v[24:25], v[12:13]
	s_cbranch_execnz .LBB0_264

; __device__ __forceinline__ void conv_weight(const float* W, int ldw, int K, int Nphys, int Nvalid, int mode, const float* g, bf16_t* WT, LAS float* scr, int gw, int NGW, int lane, int& rot) {
;     ...
; #pragma unroll
;         for (int i = 0; i < 32; ++i) { const int kk = 2 * i + (lane >> 5); float v = wv_[i]; if (g) v *= g[k0 + kk]; scr[kk * 33 + (lane & 31)] = v; }
.LBB0_264:
	ds_write2_b32 v10, v8, v9 offset0:156 offset1:222
	s_and_b64 vcc, exec, s[4:5]
	v_add_u32_e32 v10, 0x1000, v42
	s_cbranch_vccnz .LBB0_277
	s_ashr_i32 s17, s16, 31
	v_lshl_add_u64 v[8:9], s[16:17], 0, v[6:7]
	v_lshl_add_u64 v[8:9], v[8:9], 2, s[12:13]
	global_load_dword v11, v[8:9], off offset:192 nt
	global_load_dword v14, v[8:9], off offset:200 nt
	global_load_dword v12, v[8:9], off offset:208 nt
	global_load_dword v13, v[8:9], off offset:216 nt
	s_waitcnt vmcnt(3)
	v_mul_f32_e32 v11, v53, v11
	s_waitcnt vmcnt(2)
	v_mul_f32_e32 v14, v57, v14
	ds_write2_b32 v10, v11, v14 offset0:32 offset1:98
	s_waitcnt vmcnt(0)
	v_pk_mul_f32 v[8:9], v[26:27], v[12:13]
	s_cbranch_execnz .LBB0_267

; __device__ __forceinline__ void conv_weight(const float* W, int ldw, int K, int Nphys, int Nvalid, int mode, const float* g, bf16_t* WT, LAS float* scr, int gw, int NGW, int lane, int& rot) {
;     ...
; #pragma unroll
;         for (int i = 0; i < 32; ++i) { const int kk = 2 * i + (lane >> 5); float v = wv_[i]; if (g) v *= g[k0 + kk]; scr[kk * 33 + (lane & 31)] = v; }
.LBB0_267:
	ds_write2_b32 v10, v8, v9 offset0:164 offset1:230
	s_and_b64 vcc, exec, s[4:5]
	v_add_u32_e32 v10, 0x1400, v42
	s_cbranch_vccnz .LBB0_278
	s_ashr_i32 s17, s16, 31
	v_lshl_add_u64 v[8:9], s[16:17], 0, v[6:7]
	v_lshl_add_u64 v[8:9], v[8:9], 2, s[12:13]
	global_load_dword v11, v[8:9], off offset:224 nt
	global_load_dword v14, v[8:9], off offset:232 nt
	global_load_dword v12, v[8:9], off offset:240 nt
	global_load_dword v13, v[8:9], off offset:248 nt
	s_waitcnt vmcnt(3)
	v_mul_f32_e32 v11, v55, v11
	s_waitcnt vmcnt(2)
	v_mul_f32_e32 v14, v58, v14
	ds_write2_b32 v10, v11, v14 offset0:40 offset1:106
	s_waitcnt vmcnt(0)
	v_pk_mul_f32 v[8:9], v[28:29], v[12:13]
	s_cbranch_execnz .LBB0_183
	s_branch .LBB0_182

; __device__ __forceinline__ void conv_weight(const float* W, int ldw, int K, int Nphys, int Nvalid, int mode, const float* g, bf16_t* WT, LAS float* scr, int gw, int NGW, int lane, int& rot) {
;     ...
; #pragma unroll
;         for (int i = 0; i < 32; ++i) { const int kk = 2 * i + (lane >> 5); float v = wv_[i]; if (g) v *= g[k0 + kk]; scr[kk * 33 + (lane & 31)] = v; }
.LBB0_486:
	s_or_b64 exec, exec, s[4:5]
	v_cndmask_b32_e64 v27, 0, 1, s[14:15]
	v_cmp_ne_u32_e64 s[4:5], 1, v27
	s_andn2_b64 vcc, exec, s[14:15]
	s_cbranch_vccnz .LBB0_509
	v_ashrrev_i32_e32 v27, 31, v26
	s_ashr_i32 s17, s16, 31
	v_lshl_add_u64 v[26:27], v[26:27], 2, s[10:11]
	v_lshl_add_u64 v[28:29], s[16:17], 0, v[4:5]
	v_lshl_add_u64 v[28:29], v[28:29], 2, s[10:11]
	global_load_dword v87, v[26:27], off nt
	global_load_dword v90, v[28:29], off offset:8 nt
	global_load_dword v88, v[28:29], off offset:16 nt
	global_load_dword v89, v[28:29], off offset:24 nt
	s_waitcnt vmcnt(3)
	v_mul_f32_e32 v26, v86, v87
	s_waitcnt vmcnt(2)
	v_mul_f32_e32 v28, v85, v90
	ds_write_b32 v35, v26
	s_waitcnt vmcnt(0)
	v_pk_mul_f32 v[26:27], v[24:25], v[88:89]
	ds_write_b32 v56, v28
	s_cbranch_execnz .LBB0_489

; __device__ __forceinline__ void conv_weight(const float* W, int ldw, int K, int Nphys, int Nvalid, int mode, const float* g, bf16_t* WT, LAS float* scr, int gw, int NGW, int lane, int& rot) {
;     ...
; #pragma unroll
;         for (int i = 0; i < 32; ++i) { const int kk = 2 * i + (lane >> 5); float v = wv_[i]; if (g) v *= g[k0 + kk]; scr[kk * 33 + (lane & 31)] = v; }
.LBB0_489:
	s_and_b64 vcc, exec, s[4:5]
	ds_write_b32 v40, v26
	ds_write_b32 v41, v27
	s_cbranch_vccnz .LBB0_510
	s_ashr_i32 s17, s16, 31
	s_waitcnt vmcnt(0)
	v_lshl_add_u64 v[24:25], s[16:17], 0, v[4:5]
	v_lshl_add_u64 v[24:25], v[24:25], 2, s[10:11]
	global_load_dword v28, v[24:25], off offset:32 nt
	global_load_dword v29, v[24:25], off offset:40 nt
	global_load_dword v26, v[24:25], off offset:48 nt
	global_load_dword v27, v[24:25], off offset:56 nt
	s_waitcnt vmcnt(3)
	v_mul_f32_e32 v28, v84, v28
	s_waitcnt vmcnt(2)
	v_mul_f32_e32 v29, v82, v29
	ds_write_b32 v57, v28
	ds_write_b32 v58, v29
	s_waitcnt vmcnt(0)
	v_pk_mul_f32 v[24:25], v[22:23], v[26:27]
	s_cbranch_execnz .LBB0_492

; __device__ __forceinline__ void conv_weight(const float* W, int ldw, int K, int Nphys, int Nvalid, int mode, const float* g, bf16_t* WT, LAS float* scr, int gw, int NGW, int lane, int& rot) {
;     ...
; #pragma unroll
;         for (int i = 0; i < 32; ++i) { const int kk = 2 * i + (lane >> 5); float v = wv_[i]; if (g) v *= g[k0 + kk]; scr[kk * 33 + (lane & 31)] = v; }
.LBB0_492:
	s_and_b64 vcc, exec, s[4:5]
	s_waitcnt vmcnt(0)
	ds_write_b32 v42, v24
	ds_write_b32 v43, v25
	s_cbranch_vccnz .LBB0_511
	s_ashr_i32 s17, s16, 31
	v_lshl_add_u64 v[22:23], s[16:17], 0, v[4:5]
	v_lshl_add_u64 v[22:23], v[22:23], 2, s[10:11]
	global_load_dword v26, v[22:23], off offset:64 nt
	global_load_dword v27, v[22:23], off offset:72 nt
	global_load_dword v24, v[22:23], off offset:80 nt
	global_load_dword v25, v[22:23], off offset:88 nt
	s_waitcnt vmcnt(3)
	v_mul_f32_e32 v26, v83, v26
	s_waitcnt vmcnt(2)
	v_mul_f32_e32 v27, v80, v27
	ds_write_b32 v59, v26
	ds_write_b32 v60, v27
	s_waitcnt vmcnt(0)
	v_pk_mul_f32 v[22:23], v[20:21], v[24:25]
	s_cbranch_execnz .LBB0_495

; __device__ __forceinline__ void conv_weight(const float* W, int ldw, int K, int Nphys, int Nvalid, int mode, const float* g, bf16_t* WT, LAS float* scr, int gw, int NGW, int lane, int& rot) {
;     ...
; #pragma unroll
;         for (int i = 0; i < 32; ++i) { const int kk = 2 * i + (lane >> 5); float v = wv_[i]; if (g) v *= g[k0 + kk]; scr[kk * 33 + (lane & 31)] = v; }
.LBB0_495:
	s_and_b64 vcc, exec, s[4:5]
	ds_write_b32 v44, v22
	ds_write_b32 v45, v23
	s_cbranch_vccnz .LBB0_512
	s_ashr_i32 s17, s16, 31
	v_lshl_add_u64 v[20:21], s[16:17], 0, v[4:5]
	v_lshl_add_u64 v[20:21], v[20:21], 2, s[10:11]
	global_load_dword v24, v[20:21], off offset:96 nt
	global_load_dword v25, v[20:21], off offset:104 nt
	global_load_dword v22, v[20:21], off offset:112 nt
	global_load_dword v23, v[20:21], off offset:120 nt
	s_waitcnt vmcnt(3)
	v_mul_f32_e32 v24, v81, v24
	s_waitcnt vmcnt(2)
	v_mul_f32_e32 v25, v78, v25
	ds_write_b32 v61, v24
	ds_write_b32 v62, v25
	s_waitcnt vmcnt(0)
	v_pk_mul_f32 v[20:21], v[16:17], v[22:23]
	s_cbranch_execnz .LBB0_498

; __device__ __forceinline__ void conv_weight(const float* W, int ldw, int K, int Nphys, int Nvalid, int mode, const float* g, bf16_t* WT, LAS float* scr, int gw, int NGW, int lane, int& rot) {
;     ...
; #pragma unroll
;         for (int i = 0; i < 32; ++i) { const int kk = 2 * i + (lane >> 5); float v = wv_[i]; if (g) v *= g[k0 + kk]; scr[kk * 33 + (lane & 31)] = v; }
.LBB0_498:
	s_and_b64 vcc, exec, s[4:5]
	ds_write_b32 v46, v20
	ds_write_b32 v47, v21
	s_cbranch_vccnz .LBB0_513
	s_ashr_i32 s17, s16, 31
	v_lshl_add_u64 v[16:17], s[16:17], 0, v[4:5]
	v_lshl_add_u64 v[16:17], v[16:17], 2, s[10:11]
	global_load_dword v22, v[16:17], off offset:128 nt
	global_load_dword v23, v[16:17], off offset:136 nt
	global_load_dword v20, v[16:17], off offset:144 nt
	global_load_dword v21, v[16:17], off offset:152 nt
	s_waitcnt vmcnt(3)
	v_mul_f32_e32 v22, v79, v22
	s_waitcnt vmcnt(2)
	v_mul_f32_e32 v23, v76, v23
	ds_write_b32 v63, v22
	ds_write_b32 v64, v23
	s_waitcnt vmcnt(0)
	v_pk_mul_f32 v[16:17], v[14:15], v[20:21]
	s_cbranch_execnz .LBB0_501

; __device__ __forceinline__ void conv_weight(const float* W, int ldw, int K, int Nphys, int Nvalid, int mode, const float* g, bf16_t* WT, LAS float* scr, int gw, int NGW, int lane, int& rot) {
;     ...
; #pragma unroll
;         for (int i = 0; i < 32; ++i) { const int kk = 2 * i + (lane >> 5); float v = wv_[i]; if (g) v *= g[k0 + kk]; scr[kk * 33 + (lane & 31)] = v; }
.LBB0_501:
	s_and_b64 vcc, exec, s[4:5]
	ds_write_b32 v48, v16
	ds_write_b32 v49, v17
	s_cbranch_vccnz .LBB0_514
	s_ashr_i32 s17, s16, 31
	v_lshl_add_u64 v[14:15], s[16:17], 0, v[4:5]
	v_lshl_add_u64 v[14:15], v[14:15], 2, s[10:11]
	global_load_dword v20, v[14:15], off offset:160 nt
	global_load_dword v21, v[14:15], off offset:168 nt
	global_load_dword v16, v[14:15], off offset:176 nt
	global_load_dword v17, v[14:15], off offset:184 nt
	s_waitcnt vmcnt(3)
	v_mul_f32_e32 v20, v77, v20
	s_waitcnt vmcnt(2)
	v_mul_f32_e32 v21, v74, v21
	ds_write_b32 v65, v20
	ds_write_b32 v66, v21
	s_waitcnt vmcnt(0)
	v_pk_mul_f32 v[14:15], v[12:13], v[16:17]
	s_cbranch_execnz .LBB0_504

; __device__ __forceinline__ void conv_weight(const float* W, int ldw, int K, int Nphys, int Nvalid, int mode, const float* g, bf16_t* WT, LAS float* scr, int gw, int NGW, int lane, int& rot) {
;     ...
; #pragma unroll
;         for (int i = 0; i < 32; ++i) { const int kk = 2 * i + (lane >> 5); float v = wv_[i]; if (g) v *= g[k0 + kk]; scr[kk * 33 + (lane & 31)] = v; }
.LBB0_504:
	s_and_b64 vcc, exec, s[4:5]
	ds_write_b32 v50, v14
	ds_write_b32 v51, v15
	s_cbranch_vccnz .LBB0_515
	s_ashr_i32 s17, s16, 31
	v_lshl_add_u64 v[12:13], s[16:17], 0, v[4:5]
	v_lshl_add_u64 v[12:13], v[12:13], 2, s[10:11]
	global_load_dword v16, v[12:13], off offset:192 nt
	global_load_dword v17, v[12:13], off offset:200 nt
	global_load_dword v14, v[12:13], off offset:208 nt
	global_load_dword v15, v[12:13], off offset:216 nt
	s_waitcnt vmcnt(3)
	v_mul_f32_e32 v16, v75, v16
	s_waitcnt vmcnt(2)
	v_mul_f32_e32 v17, v73, v17
	ds_write_b32 v67, v16
	ds_write_b32 v68, v17
	s_waitcnt vmcnt(0)
	v_pk_mul_f32 v[12:13], v[10:11], v[14:15]
	s_cbranch_execnz .LBB0_507

; __device__ __forceinline__ void conv_weight(const float* W, int ldw, int K, int Nphys, int Nvalid, int mode, const float* g, bf16_t* WT, LAS float* scr, int gw, int NGW, int lane, int& rot) {
;     ...
; #pragma unroll
;         for (int i = 0; i < 32; ++i) { const int kk = 2 * i + (lane >> 5); float v = wv_[i]; if (g) v *= g[k0 + kk]; scr[kk * 33 + (lane & 31)] = v; }
.LBB0_507:
	s_and_b64 vcc, exec, s[4:5]
	ds_write_b32 v52, v12
	ds_write_b32 v53, v13
	s_cbranch_vccnz .LBB0_516
	s_ashr_i32 s17, s16, 31
	v_lshl_add_u64 v[10:11], s[16:17], 0, v[4:5]
	v_lshl_add_u64 v[10:11], v[10:11], 2, s[10:11]
	global_load_dword v14, v[10:11], off offset:224 nt
	global_load_dword v15, v[10:11], off offset:232 nt
	global_load_dword v12, v[10:11], off offset:240 nt
	global_load_dword v13, v[10:11], off offset:248 nt
	s_waitcnt vmcnt(3)
	v_mul_f32_e32 v14, v72, v14
	s_waitcnt vmcnt(2)
	v_mul_f32_e32 v15, v71, v15
	ds_write_b32 v69, v14
	ds_write_b32 v70, v15
	s_waitcnt vmcnt(0)
	v_pk_mul_f32 v[10:11], v[8:9], v[12:13]
	s_cbranch_execnz .LBB0_419
	s_branch .LBB0_418
